# in-proj GEMM: half of the workgroups start ~4us later (s_sleep) so epilogue store bursts interleave
# speedup vs baseline: 1.0054x; 1.0054x over previous
.LBB0_349:
	s_or_b64 exec, exec, s[0:1]
	v_readlane_b32 s0, v254, 53
	v_readlane_b32 s1, v254, 54
	s_mov_b32 s1, s97
	v_writelane_b32 v254, s0, 53
	s_waitcnt lgkmcnt(0)
	s_barrier
	v_writelane_b32 v254, s1, 54
	s_mov_b32 s0, s33
	v_mbcnt_lo_u32_b32 v5, -1, 0
	v_mbcnt_hi_u32_b32 v5, -1, v5
	s_nop 0
	v_lshl_or_b32 v0, s0, 6, v5
	v_readlane_b32 s0, v253, 36
	v_readlane_b32 s1, v253, 37
	s_andn2_b64 vcc, exec, s[0:1]
	v_readfirstlane_b32 s0, v0
	s_cbranch_vccnz .LBB0_451
	s_and_b32 s3, s28, 8
	s_cmp_eq_u32 s3, 0
	s_cbranch_scc1 .Lstag_in_skip
	s_sleep 127
.Lstag_in_skip:
	v_lshlrev_b32_e32 v1, 4, v0
	v_add_u32_e32 v2, 0x2000, v1
	v_ashrrev_i32_e32 v3, 31, v2
	v_lshrrev_b32_e32 v3, 22, v3
	v_add_u32_e32 v3, v2, v3
	v_ashrrev_i32_e32 v4, 10, v3
	v_mul_i32_i24_e32 v6, 0x400, v4
	v_sub_u32_e32 v2, v2, v6
	v_lshrrev_b32_e32 v6, 4, v2
	v_bitop3_b32 v2, v6, v2, 32 bitop3:0x6c
	v_ashrrev_i32_e32 v6, 31, v2
	v_lshrrev_b32_e32 v6, 26, v6
	v_add_u32_e32 v7, v2, v6
	v_ashrrev_i32_e32 v6, 6, v7
	v_and_b32_e32 v7, 0xc0, v7
	v_sub_u32_e32 v2, v2, v7
	v_mov_b32_e32 v10, 1
	v_lshlrev_b32_e32 v3, 5, v4
	v_ashrrev_i16_sdwa v2, v10, sext(v2) dst_sel:DWORD dst_unused:UNUSED_PAD src0_sel:DWORD src1_sel:BYTE_0
	v_and_b32_e32 v3, 32, v3
	v_bfe_i32 v7, v2, 0, 16
	v_add_u32_e32 v2, v3, v7
	v_lshlrev_b32_e32 v3, 3, v4
	v_and_b32_e32 v3, 0x1ffff0, v3
	v_add_lshl_u32 v3, v6, v3, 11
	v_lshl_add_u32 v130, v2, 1, v3
	v_ashrrev_i32_e32 v2, 31, v0
	v_lshrrev_b32_e32 v2, 26, v2
	v_add_u32_e32 v2, v0, v2
	v_bfe_i32 v0, v0, 27, 1
	v_lshrrev_b32_e32 v0, 22, v0
	v_add_u32_e32 v0, v1, v0
	v_and_b32_e32 v0, 0xfffffc00, v0
	v_sub_u32_e32 v0, v1, v0
	v_lshrrev_b32_e32 v1, 4, v0
	v_bitop3_b32 v0, v1, v0, 32 bitop3:0x6c
	v_ashrrev_i32_e32 v1, 31, v0
	v_readlane_b32 s4, v254, 53
	v_lshrrev_b32_e32 v1, 26, v1
	s_mul_hi_u32 s1, s4, 0x600000
	s_mul_i32 s3, s4, 0x600000
	v_readlane_b32 s4, v253, 7
	v_add_u32_e32 v1, v0, v1
	s_add_u32 s66, s4, s3
	v_readlane_b32 s3, v253, 6
	v_ashrrev_i32_e32 v9, 6, v1
	v_and_b32_e32 v1, 0xc0, v1
	s_addc_u32 s67, s3, s1
	s_ashr_i32 s4, s0, 6
	v_ashrrev_i32_e32 v8, 6, v2
	v_sub_u32_e32 v0, v0, v1
	s_ashr_i32 s1, s0, 8
	s_lshl_b32 s8, s4, 10
	v_lshlrev_b32_e32 v2, 5, v8
	v_ashrrev_i16_sdwa v0, v10, sext(v0) dst_sel:DWORD dst_unused:UNUSED_PAD src0_sel:DWORD src1_sel:BYTE_0
	v_lshlrev_b32_e32 v1, 3, v8
	v_readlane_b32 s6, v254, 19
	v_and_b32_e32 v2, 32, v2
	v_bfe_i32 v10, v0, 0, 16
	v_and_b32_e32 v1, 0x1ffff0, v1
	v_readlane_b32 s7, v254, 20
	s_add_u32 s60, s66, s6
	v_add_u32_e32 v0, v2, v10
	v_add_lshl_u32 v1, v9, v1, 11
	s_addc_u32 s61, s67, s7
	s_add_i32 s9, s8, 0
	v_lshl_add_u32 v12, v0, 1, v1
	s_add_i32 m0, s9, 0x10000
	v_readlane_b32 s10, v254, 25
	global_load_lds_dwordx4 v12, s[60:61]
	s_add_i32 m0, s9, 0x12000
	s_add_u32 s6, s60, 0x40000
	global_load_lds_dwordx4 v130, s[60:61]
	s_addc_u32 s7, s61, 0
	s_add_i32 m0, s9, 0x14000
	s_add_i32 s3, s9, 0x2000
	global_load_lds_dwordx4 v12, s[6:7]
	s_add_i32 m0, s9, 0x16000
	v_readlane_b32 s11, v254, 26
	global_load_lds_dwordx4 v130, s[6:7]
	v_readlane_b32 s6, v254, 23
	s_mov_b32 m0, s9
	v_readlane_b32 s7, v254, 24
	v_readlane_b32 s5, v254, 54
	v_mov_b32_e32 v131, v13
	s_mov_b64 s[62:63], s[86:87]
	s_mov_b64 s[58:59], s[82:83]
	s_mov_b64 s[56:57], s[80:81]
	global_load_lds_dwordx4 v12, s[6:7]
	s_mov_b32 m0, s3
	s_mov_b64 s[26:27], s[78:79]
	global_load_lds_dwordx4 v130, s[6:7]
	s_add_i32 s6, s9, 0x4000
	s_mov_b32 m0, s6
	s_add_i32 s7, s9, 0x6000
	global_load_lds_dwordx4 v12, s[10:11]
	s_mov_b32 m0, s7
	s_cmp_eq_u32 s1, 1
	global_load_lds_dwordx4 v130, s[10:11]
	s_cselect_b64 s[10:11], -1, 0
	v_writelane_b32 v254, s10, 60
	s_mov_b32 s25, s72
	s_mov_b32 s17, s75
	s_mov_b32 s16, s73
	v_lshl_add_u64 v[0:1], s[60:61], 0, v[12:13]
	v_writelane_b32 v254, s11, 61
	s_cmp_lg_u32 s1, 1
	v_lshl_add_u64 v[2:3], s[60:61], 0, v[130:131]
	s_cbranch_scc1 .LBB0_352
	s_barrier
